# ada pre-pass / nloc poll loops without s_sleep
# baseline (speedup 1.0000x reference)
.Lnx_odd_poll:
	global_load_dword v180, v196, s[70:71] offset:0 sc1
	global_load_dword v181, v196, s[70:71] offset:256 sc1
	global_load_dword v182, v196, s[70:71] offset:512 sc1
	global_load_dword v183, v196, s[70:71] offset:768 sc1
	global_load_dword v184, v196, s[70:71] offset:1024 sc1
	global_load_dword v185, v196, s[70:71] offset:1280 sc1
	global_load_dword v186, v196, s[70:71] offset:1536 sc1
	global_load_dword v187, v196, s[70:71] offset:1792 sc1
	global_load_dword v188, v196, s[70:71] offset:2048 sc1
	global_load_dword v189, v196, s[70:71] offset:2304 sc1
	global_load_dword v190, v196, s[70:71] offset:2560 sc1
	global_load_dword v191, v196, s[70:71] offset:2816 sc1
	global_load_dword v192, v196, s[70:71] offset:3072 sc1
	global_load_dword v193, v196, s[70:71] offset:3328 sc1
	global_load_dword v194, v196, s[70:71] offset:3584 sc1
	global_load_dword v195, v196, s[70:71] offset:3840 sc1
	s_add_i32 s73, s73, 1
	s_waitcnt vmcnt(0)
	v_add3_u32 v197, v180, v181, v182
	v_add3_u32 v197, v197, v183, v184
	v_add3_u32 v197, v197, v185, v186
	v_add3_u32 v197, v197, v187, v188
	v_add3_u32 v197, v197, v189, v190
	v_add3_u32 v197, v197, v191, v192
	v_add3_u32 v197, v197, v193, v194
	v_add_u32_e32 v197, v197, v195
	v_cmp_eq_u32_e32 vcc, s96, v197
	s_cbranch_vccnz .Lnx_odd_done
	s_cmp_lt_u32 s73, 0x8000
	s_cbranch_scc1 .Lnx_odd_poll

.Lp0a2_odd_poll:
	global_load_dword v82, v132, s[70:71] sc1
	s_add_i32 s73, s73, 1
	s_waitcnt vmcnt(0)
	v_readfirstlane_b32 s93, v82
	s_cmp_ge_u32 s93, 576
	s_cbranch_scc1 .Lp0a2_odd_ok
	s_cmp_lt_u32 s73, 0x8000
	s_cbranch_scc1 .Lp0a2_odd_poll
